# v43 + combined attention in-loop tweaks: K-fragment reads hoisted, FoX pointer math via per-unit bases, fk reads ahead of V reads with a counted wait
# speedup vs baseline: 1.0007x; 1.0007x over previous
; #define LAS __attribute__((address_space(3)))
; template <int TY> __device__ __forceinline__ void attn_unit(LAS unsigned char* lds, const AttnArgs& a, int b, int h, int qt, int wave_s) {
;     ...
;         { const int Jn = J + 2 <= J1 ? J + 2 : J1; if (hf == 0) ATT_LOAD(A, Jn); else ATT_LOAD(B, Jn); }
;         const bool skip = (64 * J > ewhi) || (TY == 0 && 64 * J + 63 + 127 < ewlo);
;         if (!skip) {
;         int lim[2]; f32x4 cinit[2];
; #pragma unroll
;         for (int qb = 0; qb < 2; ++qb) {
;             lim[qb] = eq[qb] - 64 * J - 4 * fq;
;             const float c0 = TY == 0 ? -(mrun[qb] + slope2 * (float)lim[qb]) : -mrun[qb];
;             cinit[qb] = (f32x4){c0, c0, c0, c0};
;         }
;         f32x4 s[2][4];
;         bf16x8 kfr[4][NDS];
; #pragma unroll
;         for (int kb = 0; kb < 4; ++kb)
; #pragma unroll
;             for (int ds = 0; ds < NDS; ++ds) kfr[kb][ds] = *(const LAS bf16x8*)(sb + koff + (kb * NDS + ds) * 1024);
; #pragma unroll
;         for (int kb = 0; kb < 4; ++kb) {
; #pragma unroll
;             for (int ds = 0; ds < NDS; ++ds) {
;                 s[0][kb] = __builtin_amdgcn_mfma_f32_16x16x32_bf16(kfr[kb][ds], qf[0][ds], ds == 0 ? cinit[0] : s[0][kb], 0, 0, 0);
;                 s[1][kb] = __builtin_amdgcn_mfma_f32_16x16x32_bf16(kfr[kb][ds], qf[1][ds], ds == 0 ? cinit[1] : s[1][kb], 0, 0, 0);
;             }
;         }
;         bf16x8 vf[4][2];
; #pragma unroll
;         for (int db = 0; db < 4; ++db)
; #pragma unroll
;             for (int G = 0; G < 2; ++G) {
;                 LAS unsigned char* vp = sb + voff + (32 * G * VSTR + 16 * db) * 2;
;                 const v4i16_t lo = __builtin_amdgcn_ds_read_tr16_b64_v4i16((LAS v4i16_t*)vp), hi = __builtin_amdgcn_ds_read_tr16_b64_v4i16((LAS v4i16_t*)(vp + 16 * VSTR * 2));
;                 vf[db][G] = (bf16x8){lo[0], lo[1], lo[2], lo[3], hi[0], hi[1], hi[2], hi[3]};
;             }
;         if (TY == 1) {
; #pragma unroll
;             for (int kb = 0; kb < 4; ++kb) {
;                 const f32x4 fk = *(const LAS f32x4*)(sb + KBYTES + VBYTES + (16 * kb + 4 * fq) * 4);
;                 s[0][kb] -= fk; s[1][kb] -= fk;
;             }
;         }
.LBB0_763:
	s_add_i32 s24, s22, -3
	s_cmp_le_u32 s24, s20
	s_cselect_b64 s[8:9], -1, 0
	s_and_b64 vcc, exec, s[8:9]
	s_cbranch_vccz .LBB0_777
	ds_read_b128 v[90:93], v186
	ds_read_b128 v[94:97], v186 offset:1024
	ds_read_b128 v[98:101], v186 offset:2048
	ds_read_b128 v[102:105], v186 offset:3072
	ds_read_b128 v[106:109], v186 offset:4096
	ds_read_b128 v[110:113], v186 offset:5120
	ds_read_b128 v[114:117], v186 offset:6144
	ds_read_b128 v[118:121], v186 offset:7168
	s_add_i32 s10, s22, -1
	s_min_i32 s10, s10, s20
	s_lshl_b32 s25, s10, 6
	s_mul_i32 s100, s25, s40
	s_mov_b32 s101, 0
	v_lshl_add_u64 v[10:11], s[100:101], 0, v[236:237]
	v_lshl_add_u64 v[12:13], s[100:101], 0, v[238:239]
	global_load_dwordx4 v[70:73], v[10:11], off
	global_load_dwordx4 v[74:77], v[12:13], off
	s_lshl_b32 s100, s25, 5
	v_lshl_add_u64 v[10:11], s[100:101], 0, v[240:241]
	global_load_dword v189, v[10:11], off
	s_add_i32 s10, s23, 0xffffff81
	s_cmp_gt_i32 s10, s21
	s_cbranch_scc1 .LBB0_772
	v_xor_b32_e32 v10, 0x80000000, v167
	v_xor_b32_e32 v14, 0x80000000, v166
	v_mov_b32_e32 v11, v10
	v_mov_b32_e32 v12, v10
	v_mov_b32_e32 v13, v10
	v_mov_b32_e32 v15, v14
	v_mov_b32_e32 v16, v14
	v_mov_b32_e32 v17, v14
	s_waitcnt lgkmcnt(7)
	v_mfma_f32_16x16x32_bf16 v[122:125], v[90:93], v[38:41], v[10:13]
	s_sub_i32 s10, s23, 64
	s_cmp_gt_i32 s10, s17
	s_mov_b64 s[10:11], -1
	v_mfma_f32_16x16x32_bf16 v[90:93], v[90:93], v[46:49], v[14:17]
	s_waitcnt lgkmcnt(6)
	v_mfma_f32_16x16x32_bf16 v[126:129], v[94:97], v[42:45], v[122:125]
	v_mfma_f32_16x16x32_bf16 v[130:133], v[94:97], v[50:53], v[90:93]
	s_waitcnt lgkmcnt(5)
	v_mfma_f32_16x16x32_bf16 v[90:93], v[98:101], v[38:41], v[10:13]
	v_mfma_f32_16x16x32_bf16 v[94:97], v[98:101], v[46:49], v[14:17]
	s_waitcnt lgkmcnt(4)
	v_mfma_f32_16x16x32_bf16 v[146:149], v[102:105], v[42:45], v[90:93]
	v_mfma_f32_16x16x32_bf16 v[190:193], v[102:105], v[50:53], v[94:97]
	s_waitcnt lgkmcnt(3)
	v_mfma_f32_16x16x32_bf16 v[90:93], v[106:109], v[38:41], v[10:13]
	v_mfma_f32_16x16x32_bf16 v[94:97], v[106:109], v[46:49], v[14:17]
	s_waitcnt lgkmcnt(1)
	v_mfma_f32_16x16x32_bf16 v[10:13], v[114:117], v[38:41], v[10:13]
	v_mfma_f32_16x16x32_bf16 v[14:17], v[114:117], v[46:49], v[14:17]
	v_mfma_f32_16x16x32_bf16 v[194:197], v[110:113], v[42:45], v[90:93]
	v_mfma_f32_16x16x32_bf16 v[122:125], v[110:113], v[50:53], v[94:97]
	s_waitcnt lgkmcnt(0)
	v_mfma_f32_16x16x32_bf16 v[140:143], v[118:121], v[42:45], v[10:13]
	v_mfma_f32_16x16x32_bf16 v[136:139], v[118:121], v[50:53], v[14:17]
	ds_read_b128 v[216:219], v188 offset:18432
	ds_read_b128 v[220:223], v188 offset:18496
	ds_read_b128 v[224:227], v188 offset:18560
	ds_read_b128 v[228:231], v188 offset:18624
	ds_read_b64_tr_b16 v[94:95], v187 offset:8192
	s_nop 0
	ds_read_b64_tr_b16 v[10:11], v187 offset:8224
	ds_read_b64_tr_b16 v[96:97], v187 offset:10752
	ds_read_b64_tr_b16 v[90:91], v187 offset:13312
	ds_read_b64_tr_b16 v[92:93], v187 offset:15872
	ds_read_b64_tr_b16 v[12:13], v187 offset:10784
	ds_read_b64_tr_b16 v[14:15], v187 offset:13344
	ds_read_b64_tr_b16 v[16:17], v187 offset:15904
	ds_read_b64_tr_b16 v[102:103], v187 offset:8256
	ds_read_b64_tr_b16 v[104:105], v187 offset:10816
	ds_read_b64_tr_b16 v[98:99], v187 offset:13376
	ds_read_b64_tr_b16 v[100:101], v187 offset:15936
	ds_read_b64_tr_b16 v[106:107], v187 offset:8288
	ds_read_b64_tr_b16 v[108:109], v187 offset:10848
	ds_read_b64_tr_b16 v[110:111], v187 offset:13408
	ds_read_b64_tr_b16 v[112:113], v187 offset:15968
	s_waitcnt lgkmcnt(15)
	s_cselect_b32 s99, 1, 0
	s_bitcmp1_b32 s41, 8
	s_cbranch_scc1 .Lfx_h0p1_end
	s_cmp_ge_u32 s24, s20
	s_cbranch_scc1 .Lfx_h0p1_bar
	s_waitcnt vmcnt(5)
	ds_write_b128 v182, v[62:65] offset:18688
	s_waitcnt vmcnt(4)
	ds_write_b128 v183, v[66:69] offset:26880
	s_and_saveexec_b64 s[100:101], s[4:5]
	s_cbranch_execz .Lfx_h0p1_w
	s_waitcnt vmcnt(3)
	ds_write_b32 v184, v185 offset:37120

; #define LAS __attribute__((address_space(3)))
; template <int TY> __device__ __forceinline__ void attn_unit(LAS unsigned char* lds, const AttnArgs& a, int b, int h, int qt, int wave_s) {
;     ...
;         { const int Jn = J + 2 <= J1 ? J + 2 : J1; if (hf == 0) ATT_LOAD(A, Jn); else ATT_LOAD(B, Jn); }
;         const bool skip = (64 * J > ewhi) || (TY == 0 && 64 * J + 63 + 127 < ewlo);
;         if (!skip) {
;         int lim[2]; f32x4 cinit[2];
; #pragma unroll
;         for (int qb = 0; qb < 2; ++qb) {
;             lim[qb] = eq[qb] - 64 * J - 4 * fq;
;             const float c0 = TY == 0 ? -(mrun[qb] + slope2 * (float)lim[qb]) : -mrun[qb];
;             cinit[qb] = (f32x4){c0, c0, c0, c0};
;         }
;         f32x4 s[2][4];
;         bf16x8 kfr[4][NDS];
; #pragma unroll
;         for (int kb = 0; kb < 4; ++kb)
; #pragma unroll
;             for (int ds = 0; ds < NDS; ++ds) kfr[kb][ds] = *(const LAS bf16x8*)(sb + koff + (kb * NDS + ds) * 1024);
; #pragma unroll
;         for (int kb = 0; kb < 4; ++kb) {
; #pragma unroll
;             for (int ds = 0; ds < NDS; ++ds) {
;                 s[0][kb] = __builtin_amdgcn_mfma_f32_16x16x32_bf16(kfr[kb][ds], qf[0][ds], ds == 0 ? cinit[0] : s[0][kb], 0, 0, 0);
;                 s[1][kb] = __builtin_amdgcn_mfma_f32_16x16x32_bf16(kfr[kb][ds], qf[1][ds], ds == 0 ? cinit[1] : s[1][kb], 0, 0, 0);
;             }
;         }
;         bf16x8 vf[4][2];
; #pragma unroll
;         for (int db = 0; db < 4; ++db)
; #pragma unroll
;             for (int G = 0; G < 2; ++G) {
;                 LAS unsigned char* vp = sb + voff + (32 * G * VSTR + 16 * db) * 2;
;                 const v4i16_t lo = __builtin_amdgcn_ds_read_tr16_b64_v4i16((LAS v4i16_t*)vp), hi = __builtin_amdgcn_ds_read_tr16_b64_v4i16((LAS v4i16_t*)(vp + 16 * VSTR * 2));
;                 vf[db][G] = (bf16x8){lo[0], lo[1], lo[2], lo[3], hi[0], hi[1], hi[2], hi[3]};
;             }
;         if (TY == 1) {
; #pragma unroll
;             for (int kb = 0; kb < 4; ++kb) {
;                 const f32x4 fk = *(const LAS f32x4*)(sb + KBYTES + VBYTES + (16 * kb + 4 * fq) * 4);
;                 s[0][kb] -= fk; s[1][kb] -= fk;
;             }
;         }
.LBB0_777:
	s_andn2_b64 vcc, exec, s[8:9]
	s_cbranch_vccnz .LBB0_762
	s_cmp_ge_u32 s24, s20
	s_cbranch_scc1 .LBB0_762
	ds_read_b128 v[90:93], v186 offset:18688
	ds_read_b128 v[94:97], v186 offset:19712
	ds_read_b128 v[98:101], v186 offset:20736
	ds_read_b128 v[102:105], v186 offset:21760
	ds_read_b128 v[106:109], v186 offset:22784
	ds_read_b128 v[110:113], v186 offset:23808
	ds_read_b128 v[114:117], v186 offset:24832
	ds_read_b128 v[118:121], v186 offset:25856
	s_min_i32 s8, s22, s20
	s_lshl_b32 s10, s8, 6
	s_mul_i32 s100, s10, s40
	s_mov_b32 s101, 0
	v_lshl_add_u64 v[10:11], s[100:101], 0, v[236:237]
	v_lshl_add_u64 v[12:13], s[100:101], 0, v[238:239]
	global_load_dwordx4 v[62:65], v[10:11], off
	global_load_dwordx4 v[66:69], v[12:13], off
	s_lshl_b32 s100, s10, 5
	v_lshl_add_u64 v[10:11], s[100:101], 0, v[240:241]
	global_load_dword v185, v[10:11], off
	s_sub_i32 s8, s23, 63
	s_cmp_gt_i32 s8, s21
	s_cbranch_scc1 .LBB0_787
	v_xor_b32_e32 v10, 0x80000000, v167
	v_xor_b32_e32 v14, 0x80000000, v166
	v_mov_b32_e32 v11, v10
	v_mov_b32_e32 v12, v10
	v_mov_b32_e32 v13, v10
	v_mov_b32_e32 v15, v14
	v_mov_b32_e32 v16, v14
	v_mov_b32_e32 v17, v14
	s_waitcnt lgkmcnt(7)
	v_mfma_f32_16x16x32_bf16 v[122:125], v[90:93], v[38:41], v[10:13]
	s_cmp_gt_i32 s23, s17
	s_mov_b64 s[8:9], -1
	v_mfma_f32_16x16x32_bf16 v[90:93], v[90:93], v[46:49], v[14:17]
	s_waitcnt lgkmcnt(6)
	v_mfma_f32_16x16x32_bf16 v[126:129], v[94:97], v[42:45], v[122:125]
	v_mfma_f32_16x16x32_bf16 v[130:133], v[94:97], v[50:53], v[90:93]
	s_waitcnt lgkmcnt(5)
	v_mfma_f32_16x16x32_bf16 v[90:93], v[98:101], v[38:41], v[10:13]
	v_mfma_f32_16x16x32_bf16 v[94:97], v[98:101], v[46:49], v[14:17]
	s_waitcnt lgkmcnt(4)
	v_mfma_f32_16x16x32_bf16 v[146:149], v[102:105], v[42:45], v[90:93]
	v_mfma_f32_16x16x32_bf16 v[190:193], v[102:105], v[50:53], v[94:97]
	s_waitcnt lgkmcnt(3)
	v_mfma_f32_16x16x32_bf16 v[90:93], v[106:109], v[38:41], v[10:13]
	v_mfma_f32_16x16x32_bf16 v[94:97], v[106:109], v[46:49], v[14:17]
	s_waitcnt lgkmcnt(1)
	v_mfma_f32_16x16x32_bf16 v[10:13], v[114:117], v[38:41], v[10:13]
	v_mfma_f32_16x16x32_bf16 v[14:17], v[114:117], v[46:49], v[14:17]
	v_mfma_f32_16x16x32_bf16 v[194:197], v[110:113], v[42:45], v[90:93]
	v_mfma_f32_16x16x32_bf16 v[122:125], v[110:113], v[50:53], v[94:97]
	s_waitcnt lgkmcnt(0)
	v_mfma_f32_16x16x32_bf16 v[140:143], v[118:121], v[42:45], v[10:13]
	v_mfma_f32_16x16x32_bf16 v[136:139], v[118:121], v[50:53], v[14:17]
	ds_read_b128 v[216:219], v188 offset:37120
	ds_read_b128 v[220:223], v188 offset:37184
	ds_read_b128 v[224:227], v188 offset:37248
	ds_read_b128 v[228:231], v188 offset:37312
	ds_read_b64_tr_b16 v[94:95], v187 offset:26880
	s_nop 0
	ds_read_b64_tr_b16 v[10:11], v187 offset:26912
	ds_read_b64_tr_b16 v[96:97], v187 offset:29440
	ds_read_b64_tr_b16 v[90:91], v187 offset:32000
	ds_read_b64_tr_b16 v[92:93], v187 offset:34560
	ds_read_b64_tr_b16 v[12:13], v187 offset:29472
	ds_read_b64_tr_b16 v[14:15], v187 offset:32032
	ds_read_b64_tr_b16 v[16:17], v187 offset:34592
	ds_read_b64_tr_b16 v[102:103], v187 offset:26944
	ds_read_b64_tr_b16 v[104:105], v187 offset:29504
	ds_read_b64_tr_b16 v[98:99], v187 offset:32064
	ds_read_b64_tr_b16 v[100:101], v187 offset:34624
	ds_read_b64_tr_b16 v[106:107], v187 offset:26976
	ds_read_b64_tr_b16 v[108:109], v187 offset:29536
	ds_read_b64_tr_b16 v[110:111], v187 offset:32096
	ds_read_b64_tr_b16 v[112:113], v187 offset:34656
	s_waitcnt lgkmcnt(15)
	s_cselect_b32 s99, 1, 0
	s_bitcmp1_b32 s41, 8
	s_cbranch_scc1 .Lfx_h1p1_end
	s_add_i32 s100, s22, -2
	s_cmp_ge_u32 s100, s20
	s_cbranch_scc1 .Lfx_h1p1_bar
	s_waitcnt vmcnt(5)
	ds_write_b128 v182, v[70:73]
	s_waitcnt vmcnt(4)
	ds_write_b128 v183, v[74:77] offset:8192
	s_and_saveexec_b64 s[100:101], s[4:5]
	s_cbranch_execz .Lfx_h1p1_w
	s_waitcnt vmcnt(3)
	ds_write_b32 v184, v189 offset:18432
